# attention unit prologues: Q fragment loads issued together with counted vmcnt waits
# baseline (speedup 1.0000x reference)
; #define SLOAD(i, k0) do { sr_[i].vs0 = ld8(&Vg[(long)((k0) + sr) * LDP + sc]); sr_[i].vs1 = ld8(&Vg[(long)((k0) + 32 + sr) * LDP + sc]); \
;     sr_[i].ks0 = ld8(&Kg[(long)((k0) + sr) * LDP + sc]); sr_[i].ks1 = ld8(&Kg[(long)((k0) + 32 + sr) * LDP + sc]); } while (0)
; #define SWRITE(off, i) do { *(bf16x8*)(V_lds + (off) + vst0) = sr_[i].vs0;          \
;     *(bf16x8*)(V_lds + (off) + vst1) = sr_[i].vs1; int kc = sc * 2;               \
;     *(bf16x8*)(K_lds + (off) + KSWZ(sr, kc)) = sr_[i].ks0;                       \
;     *(bf16x8*)(K_lds + (off) + KSWZ(32 + sr, kc)) = sr_[i].ks1; } while (0)
; template <int MODE, int ORD> ...
;     ...
;   const bf16* Qw = Qb + (long)(wq * 32 + r32) * LDP + cst * 64 + hi * 8;
; #pragma unroll
;   for (int d0 = 0; d0 < ND0; ++d0) qr[d0] = scale_bf16x8(ld8(Qw + d0 * 16), C);
;     ...
;   SLOAD(SE, 0); asm volatile("s_waitcnt vmcnt(0)" ::: "memory"); SWRITE(0, SE); __syncthreads();
.LBB0_157:
	s_or_b64 exec, exec, s[0:1]
	s_lshl_b32 s68, s6, 7
	s_add_u32 s6, s10, s68
	s_addc_u32 s7, s11, 0
	s_mul_i32 s0, s7, 0x2400
	s_mul_hi_u32 s1, s6, 0x2400
	s_add_i32 s1, s1, s0
	s_mul_i32 s0, s6, 0x2400
	s_add_u32 s0, s20, s0
	s_addc_u32 s1, s21, s1
	s_lshl_b32 s78, s80, 8
	s_add_u32 s0, s0, s78
	s_mul_i32 s18, s11, 0x2400
	s_mul_hi_u32 s19, s10, 0x2400
	s_addc_u32 s1, s1, 0
	s_add_i32 s19, s19, s18
	s_mul_i32 s18, s10, 0x2400
	s_add_u32 s18, s20, s18
	s_addc_u32 s19, s21, s19
	s_add_u32 s18, s18, s78
	s_addc_u32 s19, s19, 0
	s_add_u32 s42, s18, 0x1000
	s_addc_u32 s43, s19, 0
	s_and_b32 s66, s62, 3
	v_and_b32_e32 v184, 31, v40
	s_lshl_b32 s79, s66, 5
	v_or_b32_e32 v0, s79, v184
	v_mul_u32_u24_e32 v0, 0x1200, v0
	s_ashr_i32 s64, s63, 8
	v_lshlrev_b32_e32 v204, 1, v0
	v_lshl_add_u64 v[0:1], s[0:1], 0, v[204:205]
	s_lshl_b32 s0, s64, 6
	v_bfe_u32 v185, v40, 5, 1
	s_ashr_i32 s1, s0, 31
	v_lshl_add_u64 v[0:1], s[0:1], 1, v[0:1]
	v_lshlrev_b32_e32 v204, 4, v185
	v_lshl_add_u64 v[4:5], v[0:1], 0, v[204:205]
	global_load_dwordx4 v[0:3], v[4:5], off
	global_load_dwordx4 v[64:67], v[4:5], off offset:32
	global_load_dwordx4 v[68:71], v[4:5], off offset:64
	global_load_dwordx4 v[72:75], v[4:5], off offset:96
	v_ashrrev_i32_e32 v38, 4, v40
	v_lshlrev_b32_e32 v16, 3, v40
	v_add_u32_e32 v17, 32, v38
	v_and_b32_e32 v41, 0x78, v16
	v_lshlrev_b32_e32 v19, 4, v40
	v_and_b32_e32 v20, 0xfffff0, v38
	v_lshlrev_b32_e32 v21, 1, v38
	v_lshrrev_b32_e32 v22, 1, v38
	v_and_b32_e32 v23, 3, v38
	v_and_b32_e32 v47, 0x70, v19
	v_and_or_b32 v19, v21, 8, v20
	v_and_or_b32 v20, v22, 4, v23
	v_and_b32_e32 v22, 0xfffff0, v17
	v_lshlrev_b32_e32 v23, 1, v17
	v_and_b32_e32 v18, 0x70, v40
	v_bfe_u32 v16, v16, 5, 2
	v_lshlrev_b32_e32 v24, 8, v38
	v_lshlrev_b32_e32 v21, 1, v41
	v_lshrrev_b32_e32 v19, 1, v19
	v_and_or_b32 v22, v23, 8, v22
	v_bitop3_b32 v191, v21, v24, v18 bitop3:0xde
	v_lshlrev_b32_e32 v20, 6, v20
	v_and_b32_e32 v23, 48, v21
	v_lshlrev_b32_e32 v39, 8, v184
	s_add_i32 s69, 0, 0x18800
	v_lshl_or_b32 v48, s64, 7, v204
	v_xad_u32 v188, v48, v47, v39
	v_add_u32_e32 v42, 0, v191
	s_or_b32 s92, s79, s68
	s_cmpk_lt_u32 s92, 0xbf
	s_cselect_b64 s[48:49], -1, 0
	v_readlane_b32 s34, v255, 35
	s_mov_b64 s[56:57], -1
	s_and_b64 vcc, exec, s[48:49]
	v_lshlrev_b32_e32 v197, 2, v185
	s_waitcnt vmcnt(3)
	v_lshlrev_b32_e32 v6, 16, v0
	v_and_b32_e32 v0, 0xffff0000, v0
	v_lshlrev_b32_e32 v7, 16, v1
	v_and_b32_e32 v1, 0xffff0000, v1
	v_lshlrev_b32_e32 v8, 16, v2
	v_and_b32_e32 v2, 0xffff0000, v2
	v_lshlrev_b32_e32 v9, 16, v3
	v_and_b32_e32 v3, 0xffff0000, v3
	v_mul_f32_e32 v0, 0x3e38aa3b, v0
	v_mul_f32_e32 v1, 0x3e38aa3b, v1
	v_mul_f32_e32 v2, 0x3e38aa3b, v2
	v_mul_f32_e32 v3, 0x3e38aa3b, v3
	v_mul_f32_e32 v6, 0x3e38aa3b, v6
	v_mul_f32_e32 v7, 0x3e38aa3b, v7
	v_mul_f32_e32 v8, 0x3e38aa3b, v8
	v_mul_f32_e32 v9, 0x3e38aa3b, v9
	v_cvt_pk_bf16_f32 v128, v6, v0
	v_cvt_pk_bf16_f32 v129, v7, v1
	v_cvt_pk_bf16_f32 v130, v8, v2
	v_cvt_pk_bf16_f32 v131, v9, v3
	s_waitcnt vmcnt(2)
	v_mov_b32_e32 v0, v64
	v_mov_b32_e32 v1, v65
	v_mov_b32_e32 v2, v66
	v_mov_b32_e32 v3, v67
	v_lshlrev_b32_e32 v6, 16, v0
	v_and_b32_e32 v0, 0xffff0000, v0
	v_lshlrev_b32_e32 v7, 16, v1
	v_and_b32_e32 v1, 0xffff0000, v1
	v_lshlrev_b32_e32 v8, 16, v2
	v_and_b32_e32 v2, 0xffff0000, v2
	v_lshlrev_b32_e32 v9, 16, v3
	v_and_b32_e32 v3, 0xffff0000, v3
	v_mul_f32_e32 v0, 0x3e38aa3b, v0
	v_mul_f32_e32 v1, 0x3e38aa3b, v1
	v_mul_f32_e32 v2, 0x3e38aa3b, v2
	v_mul_f32_e32 v3, 0x3e38aa3b, v3
	v_mul_f32_e32 v6, 0x3e38aa3b, v6
	v_mul_f32_e32 v7, 0x3e38aa3b, v7
	v_mul_f32_e32 v8, 0x3e38aa3b, v8
	v_mul_f32_e32 v9, 0x3e38aa3b, v9
	v_cvt_pk_bf16_f32 v132, v6, v0
	v_cvt_pk_bf16_f32 v133, v7, v1
	v_cvt_pk_bf16_f32 v134, v8, v2
	v_cvt_pk_bf16_f32 v135, v9, v3
	s_waitcnt vmcnt(1)
	v_mov_b32_e32 v0, v68
	v_mov_b32_e32 v1, v69
	v_mov_b32_e32 v2, v70
	v_mov_b32_e32 v3, v71
	v_lshlrev_b32_e32 v6, 16, v0
	v_and_b32_e32 v0, 0xffff0000, v0
	v_lshlrev_b32_e32 v7, 16, v1
	v_and_b32_e32 v1, 0xffff0000, v1
	v_lshlrev_b32_e32 v8, 16, v2
	v_and_b32_e32 v2, 0xffff0000, v2
	v_lshlrev_b32_e32 v9, 16, v3
	v_and_b32_e32 v3, 0xffff0000, v3
	v_mul_f32_e32 v0, 0x3e38aa3b, v0
	v_mul_f32_e32 v1, 0x3e38aa3b, v1
	v_mul_f32_e32 v2, 0x3e38aa3b, v2
	v_mul_f32_e32 v3, 0x3e38aa3b, v3
	v_mul_f32_e32 v6, 0x3e38aa3b, v6
	v_mul_f32_e32 v7, 0x3e38aa3b, v7
	v_mul_f32_e32 v8, 0x3e38aa3b, v8
	v_mul_f32_e32 v9, 0x3e38aa3b, v9
	v_cvt_pk_bf16_f32 v136, v6, v0
	v_cvt_pk_bf16_f32 v137, v7, v1
	v_cvt_pk_bf16_f32 v138, v8, v2
	v_cvt_pk_bf16_f32 v139, v9, v3
	v_mad_i64_i32 v[4:5], s[0:1], v38, s73, 0
	v_mad_i64_i32 v[6:7], s[0:1], v17, s73, 0
	v_or_b32_e32 v4, v4, v41
	v_or_b32_e32 v6, v6, v41
	v_lshlrev_b64 v[4:5], 1, v[4:5]
	v_lshlrev_b64 v[6:7], 1, v[6:7]
	v_lshl_add_u64 v[8:9], s[18:19], 0, v[4:5]
	v_lshl_add_u64 v[12:13], s[18:19], 0, v[6:7]
	v_lshl_add_u64 v[4:5], s[42:43], 0, v[4:5]
	v_lshl_add_u64 v[6:7], s[42:43], 0, v[6:7]
	v_lshlrev_b32_e32 v17, 8, v17
	v_bitop3_b32 v192, v21, v17, v18 bitop3:0xde
	v_or_b32_e32 v17, v19, v16
	v_lshrrev_b32_e32 v18, 1, v22
	v_lshlrev_b32_e32 v17, 9, v17
	v_or_b32_e32 v16, v18, v16
	v_lshlrev_b32_e32 v16, 9, v16
	v_or3_b32 v193, v17, v20, v23
	v_or3_b32 v194, v16, v20, v23
	v_add_u32_e32 v44, 0, v193
	v_mov_b32_e32 v16, s69
	v_add_u32_e32 v43, 0, v192
	v_add_u32_e32 v45, 0, v194
	s_waitcnt vmcnt(0)
	v_mov_b32_e32 v0, v72
	v_mov_b32_e32 v1, v73
	v_mov_b32_e32 v2, v74
	v_mov_b32_e32 v3, v75
	v_lshlrev_b32_e32 v10, 16, v0
	v_and_b32_e32 v0, 0xffff0000, v0
	v_lshlrev_b32_e32 v11, 16, v1
	v_and_b32_e32 v1, 0xffff0000, v1
	v_lshlrev_b32_e32 v14, 16, v2
	v_and_b32_e32 v2, 0xffff0000, v2
	v_lshlrev_b32_e32 v15, 16, v3
	v_and_b32_e32 v3, 0xffff0000, v3
	v_mul_f32_e32 v10, 0x3e38aa3b, v10
	v_mul_f32_e32 v0, 0x3e38aa3b, v0
	v_mul_f32_e32 v11, 0x3e38aa3b, v11
	v_mul_f32_e32 v1, 0x3e38aa3b, v1
	v_mul_f32_e32 v14, 0x3e38aa3b, v14
	v_mul_f32_e32 v2, 0x3e38aa3b, v2
	v_mul_f32_e32 v15, 0x3e38aa3b, v15
	v_mul_f32_e32 v3, 0x3e38aa3b, v3
	v_cvt_pk_bf16_f32 v140, v10, v0
	v_cvt_pk_bf16_f32 v141, v11, v1
	v_cvt_pk_bf16_f32 v142, v14, v2
	v_cvt_pk_bf16_f32 v143, v15, v3
	global_load_dwordx4 v[0:3], v[4:5], off
	s_nop 0
	global_load_dwordx4 v[4:7], v[6:7], off
	s_nop 0
	global_load_dwordx4 v[8:11], v[8:9], off offset:2048
	s_nop 0
	global_load_dwordx4 v[12:15], v[12:13], off offset:2048
	s_waitcnt vmcnt(0)
	s_waitcnt vmcnt(3)
	ds_write_b128 v44, v[0:3]
	s_waitcnt vmcnt(2)
	ds_write_b128 v45, v[4:7]
	s_waitcnt vmcnt(1)
	ds_write_b128 v42, v[8:11] offset:16384
	s_waitcnt vmcnt(0)
	ds_write_b128 v43, v[12:15] offset:16384
	s_waitcnt lgkmcnt(0)
	s_barrier
; #define SETBE(t) do { TCLS(t); const float bt_ = near_ ? 0.f : ((rmax_ <= -128) ? bL : bR); \
;     if (bt_ != be_cur) { const float d_ = bt_ - be_cur; _Pragma("unroll") for (int r = 0; r < 16; ++r) negm[r] += d_; be_cur = bt_; } } while (0)
; template <int ND0> __device__ __forceinline__ void qkt(f32x16& p0, f32x16& p1, const char* Ks, const bf16x8* qr, int r32, int hi, int cboff, const f32x16& ci) {
; #pragma unroll
;   for (int d0 = 0; d0 < ND0; ++d0) { int cb = cboff + (d0 * 16 + hi * 8) * 2;
;     bf16x8 b0 = *reinterpret_cast<const bf16x8*>(Ks + KSWZ(r32, cb));
;     bf16x8 b1 = *reinterpret_cast<const bf16x8*>(Ks + KSWZ(32 + r32, cb));
;     if (d0 == 0) { p0 = __builtin_amdgcn_mfma_f32_32x32x16_bf16(b0, qr[0], ci, 0, 0, 0); p1 = __builtin_amdgcn_mfma_f32_32x32x16_bf16(b1, qr[0], ci, 0, 0, 0); }
;     else { p0 = __builtin_amdgcn_mfma_f32_32x32x16_bf16(b0, qr[d0], p0, 0, 0, 0); p1 = __builtin_amdgcn_mfma_f32_32x32x16_bf16(b1, qr[d0], p1, 0, 0, 0); } }
; }
; template <int MODE, int ORD> ...
;     ...
;   bL = tab[0]; bR = tab[256];
;   SETBE(0); qkt<ND0>(pA0, pA1, K_lds, qr, r32, hi, cboff, negm); BIAS(pA0, pA1, 0); partialSM2<MODE == 0>(pA0, pA1, m_reg, negm, alA);
	ds_read_b32 v195, v16
	v_add_u32_e32 v16, 0, v188
	ds_read_b128 v[34:37], v16 offset:16384
	v_bfrev_b32_e32 v0, 1
	s_waitcnt lgkmcnt(1)
	v_cndmask_b32_e64 v46, v195, 0, s[48:49]
	v_cmp_neq_f32_e64 s[0:1], 0, v46
	s_nop 1
	v_cndmask_b32_e64 v0, v0, v46, s[0:1]
	v_mov_b32_e32 v1, v0
	v_mov_b32_e32 v2, v0
	v_mov_b32_e32 v3, v0
	v_mov_b32_e32 v4, v0
	v_mov_b32_e32 v5, v0
	v_mov_b32_e32 v6, v0
	v_mov_b32_e32 v7, v0
	v_mov_b32_e32 v8, v0
	v_mov_b32_e32 v9, v0
	v_mov_b32_e32 v10, v0
	v_mov_b32_e32 v11, v0
	v_mov_b32_e32 v12, v0
	v_mov_b32_e32 v13, v0
	v_mov_b32_e32 v14, v0
	v_mov_b32_e32 v15, v0
	s_waitcnt lgkmcnt(0)
	s_nop 0
	v_mfma_f32_32x32x16_bf16 v[18:33], v[34:37], v[128:131], v[0:15]
	ds_read_b128 v[34:37], v16 offset:24576
	v_or_b32_e32 v16, 32, v48
	v_xad_u32 v196, v16, v47, v39
	v_mov_b64_e32 v[16:17], v[14:15]
	v_add_u32_e32 v49, 0, v196
	s_nop 1
	v_mov_b64_e32 v[14:15], v[12:13]
	v_mov_b64_e32 v[12:13], v[10:11]
	v_mov_b64_e32 v[10:11], v[8:9]
	v_mov_b64_e32 v[8:9], v[6:7]
	v_mov_b64_e32 v[6:7], v[4:5]
	v_mov_b64_e32 v[4:5], v[2:3]
	v_mov_b64_e32 v[2:3], v[0:1]
	v_or_b32_e32 v1, 64, v48
	v_xad_u32 v190, v1, v47, v39
	s_waitcnt lgkmcnt(0)
	v_mfma_f32_32x32x16_bf16 v[2:17], v[34:37], v[128:131], v[2:17]
	ds_read_b128 v[34:37], v49 offset:16384
	v_add_u32_e32 v1, 0, v190
	s_waitcnt lgkmcnt(0)
	v_mfma_f32_32x32x16_bf16 v[18:33], v[34:37], v[132:135], v[18:33]
	ds_read_b128 v[34:37], v49 offset:24576
	s_waitcnt lgkmcnt(0)
	v_mfma_f32_32x32x16_bf16 v[2:17], v[34:37], v[132:135], v[2:17]
	ds_read_b128 v[34:37], v1 offset:16384
	s_waitcnt lgkmcnt(0)
	v_mfma_f32_32x32x16_bf16 v[18:33], v[34:37], v[136:139], v[18:33]
	ds_read_b128 v[34:37], v1 offset:24576
	v_or_b32_e32 v1, 0x60, v48
	v_xad_u32 v189, v1, v47, v39
	v_add_u32_e32 v1, 0, v189
	s_waitcnt lgkmcnt(0)
	v_mfma_f32_32x32x16_bf16 v[2:17], v[34:37], v[136:139], v[2:17]
	ds_read_b128 v[34:37], v1 offset:16384
	s_waitcnt lgkmcnt(0)
	v_mfma_f32_32x32x16_bf16 v[18:33], v[34:37], v[140:143], v[18:33]
	ds_read_b128 v[34:37], v1 offset:24576
	v_mov_b32_e32 v1, s34
	ds_read_b32 v200, v1
	s_waitcnt lgkmcnt(1)
	v_mfma_f32_32x32x16_bf16 v[2:17], v[34:37], v[140:143], v[2:17]
	s_cbranch_vccnz .LBB0_159
	v_lshlrev_b32_e32 v1, 2, v185
	s_mov_b64 s[56:57], 0

; __device__ __forceinline__ int v_st(int k, int c) { const int kk = (k & ~0xC) | ((k & 4) << 1) | ((k & 8) >> 1); return ((kk >> 3) * 4 + (c >> 5)) * 512 + ((kk & 7) * 32 + (c & 31)) * 2; }
; __device__ __forceinline__ int v_rd_base(int lane) { return ((lane & 3) << 3) | (((lane >> 2) & 3) << 6) | (((lane >> 4) & 1) << 5) | (((lane >> 5) & 1) << 8); }
; template <int MODE, int ORD> ...
;     ...
;   const bf16* Qw = Qb + (long)(wq * 32 + r32) * LDP + cst * 64 + hi * 8;
; #pragma unroll
;   for (int d0 = 0; d0 < ND0; ++d0) qr[d0] = scale_bf16x8(ld8(Qw + d0 * 16), C);
;   const int qpos = qpos0 + wq * 32 + r32;
;   const int qw0 = qpos0 + wq * 32;
;   const int cboff = cst * 128;
;   int sr = tid >> 4, sc = (tid & 15) * 8, vst0 = v_st(sr, sc), vst1 = v_st(32 + sr, sc);
;   int vb0 = (int)(uintptr_t)V_lds + v_rd_base(lane);
.LBB0_213:
	s_or_b64 exec, exec, s[0:1]
	s_add_i32 s0, s7, 0xffffff80
	s_mul_i32 s6, s4, 0x240000
	s_mul_hi_i32 s1, s4, 0x240000
	s_add_u32 s6, s20, s6
	s_addc_u32 s1, s21, s1
	s_lshl_b32 s34, s56, 8
	s_add_u32 s6, s6, s34
	s_addc_u32 s1, s1, 0
	s_add_u32 s60, s6, 0x1800
	s_addc_u32 s61, s1, 0
	s_mul_i32 s1, s19, 0x2400
	s_mul_hi_u32 s6, s18, 0x2400
	s_add_i32 s6, s6, s1
	s_mul_i32 s1, s18, 0x2400
	s_add_u32 s1, s20, s1
	s_addc_u32 s6, s21, s6
	s_lshl_b32 s19, s56, 6
	s_and_b32 s19, s19, 0x100
	s_add_u32 s1, s1, s19
	s_addc_u32 s19, s6, 0
	v_and_b32_e32 v177, 31, v48
	s_lshl_b32 s6, s42, 5
	v_bfe_u32 v176, v48, 5, 1
	v_or_b32_e32 v3, s6, v177
	v_mov_b64_e32 v[0:1], s[60:61]
	v_mad_i64_i32 v[0:1], s[42:43], v3, s53, v[0:1]
	v_lshlrev_b32_e32 v204, 4, v176
	v_lshl_add_u64 v[0:1], v[0:1], 0, v[204:205]
	global_load_dwordx4 v[4:7], v[0:1], off
	global_load_dwordx4 v[64:67], v[0:1], off offset:32
	global_load_dwordx4 v[68:71], v[0:1], off offset:64
	global_load_dwordx4 v[72:75], v[0:1], off offset:96
	global_load_dwordx4 v[76:79], v[0:1], off offset:128
	global_load_dwordx4 v[80:83], v[0:1], off offset:160
	global_load_dwordx4 v[84:87], v[0:1], off offset:192
	global_load_dwordx4 v[88:91], v[0:1], off offset:224
	v_ashrrev_i32_e32 v179, 4, v48
	v_add_u32_e32 v33, 32, v179
	s_mul_i32 s35, s0, 0x2400
	s_mul_hi_u32 s34, s0, 0x2400
	s_add_u32 s1, s1, s35
	v_or_b32_e32 v16, s57, v177
	s_addc_u32 s19, s19, s34
	s_add_u32 s96, s1, 0x2000
	v_add_u32_e32 v178, s6, v16
	s_addc_u32 s97, s19, 0
	s_add_u32 s42, s1, 0x2200
	s_addc_u32 s43, s19, 0
	v_mad_i64_i32 v[20:21], s[60:61], v33, s73, 0
	v_lshlrev_b32_e32 v53, 8, v177
	v_lshlrev_b32_e32 v191, 2, v176
	s_add_i32 s19, 0, 0x18800
	v_mov_b32_e32 v194, 1.0
	s_waitcnt vmcnt(7)
	v_lshlrev_b32_e32 v3, 16, v4
	v_and_b32_e32 v4, 0xffff0000, v4
	v_mul_f32_e32 v4, 0x3e0293ee, v4
	v_mul_f32_e32 v3, 0x3e0293ee, v3
	v_cvt_pk_bf16_f32 v128, v3, v4
	v_and_b32_e32 v4, 0xffff0000, v5
	v_lshlrev_b32_e32 v3, 16, v5
	v_mul_f32_e32 v4, 0x3e0293ee, v4
	v_mul_f32_e32 v3, 0x3e0293ee, v3
	v_cvt_pk_bf16_f32 v129, v3, v4
	v_and_b32_e32 v4, 0xffff0000, v6
	v_lshlrev_b32_e32 v3, 16, v6
	v_mul_f32_e32 v4, 0x3e0293ee, v4
	v_mul_f32_e32 v3, 0x3e0293ee, v3
	v_cvt_pk_bf16_f32 v130, v3, v4
	v_and_b32_e32 v4, 0xffff0000, v7
	v_lshlrev_b32_e32 v3, 16, v7
	v_mul_f32_e32 v4, 0x3e0293ee, v4
	v_mul_f32_e32 v3, 0x3e0293ee, v3
	v_cvt_pk_bf16_f32 v131, v3, v4
	s_waitcnt vmcnt(6)
	v_mov_b32_e32 v4, v64
	v_mov_b32_e32 v5, v65
	v_mov_b32_e32 v6, v66
	v_mov_b32_e32 v7, v67
	v_lshlrev_b32_e32 v3, 16, v4
	v_and_b32_e32 v4, 0xffff0000, v4
	v_mul_f32_e32 v4, 0x3e0293ee, v4
	v_mul_f32_e32 v3, 0x3e0293ee, v3
	v_cvt_pk_bf16_f32 v132, v3, v4
	v_and_b32_e32 v4, 0xffff0000, v5
	v_lshlrev_b32_e32 v3, 16, v5
	v_mul_f32_e32 v4, 0x3e0293ee, v4
	v_mul_f32_e32 v3, 0x3e0293ee, v3
	v_cvt_pk_bf16_f32 v133, v3, v4
	v_and_b32_e32 v4, 0xffff0000, v6
	v_lshlrev_b32_e32 v3, 16, v6
	v_mul_f32_e32 v4, 0x3e0293ee, v4
	v_mul_f32_e32 v3, 0x3e0293ee, v3
	v_cvt_pk_bf16_f32 v134, v3, v4
	v_and_b32_e32 v4, 0xffff0000, v7
	v_lshlrev_b32_e32 v3, 16, v7
	v_mul_f32_e32 v4, 0x3e0293ee, v4
	v_mul_f32_e32 v3, 0x3e0293ee, v3
	v_cvt_pk_bf16_f32 v135, v3, v4
	s_waitcnt vmcnt(5)
	v_mov_b32_e32 v4, v68
	v_mov_b32_e32 v5, v69
	v_mov_b32_e32 v6, v70
	v_mov_b32_e32 v7, v71
	v_lshlrev_b32_e32 v3, 16, v4
	v_and_b32_e32 v4, 0xffff0000, v4
	v_mul_f32_e32 v4, 0x3e0293ee, v4
	v_mul_f32_e32 v3, 0x3e0293ee, v3
	v_cvt_pk_bf16_f32 v136, v3, v4
	v_and_b32_e32 v4, 0xffff0000, v5
	v_lshlrev_b32_e32 v3, 16, v5
	v_mul_f32_e32 v4, 0x3e0293ee, v4
	v_mul_f32_e32 v3, 0x3e0293ee, v3
	v_cvt_pk_bf16_f32 v137, v3, v4
	v_and_b32_e32 v4, 0xffff0000, v6
	v_lshlrev_b32_e32 v3, 16, v6
	v_mul_f32_e32 v4, 0x3e0293ee, v4
	v_mul_f32_e32 v3, 0x3e0293ee, v3
	v_cvt_pk_bf16_f32 v138, v3, v4
	v_and_b32_e32 v4, 0xffff0000, v7
	v_lshlrev_b32_e32 v3, 16, v7
	v_mul_f32_e32 v4, 0x3e0293ee, v4
	v_mul_f32_e32 v3, 0x3e0293ee, v3
	v_cvt_pk_bf16_f32 v139, v3, v4
	s_waitcnt vmcnt(4)
	v_mov_b32_e32 v4, v72
	v_mov_b32_e32 v5, v73
	v_mov_b32_e32 v6, v74
	v_mov_b32_e32 v7, v75
	v_lshlrev_b32_e32 v3, 16, v4
	v_and_b32_e32 v4, 0xffff0000, v4
	v_mul_f32_e32 v4, 0x3e0293ee, v4
	v_mul_f32_e32 v3, 0x3e0293ee, v3
	v_cvt_pk_bf16_f32 v140, v3, v4
	v_and_b32_e32 v4, 0xffff0000, v5
	v_lshlrev_b32_e32 v3, 16, v5
	v_mul_f32_e32 v4, 0x3e0293ee, v4
	v_mul_f32_e32 v3, 0x3e0293ee, v3
	v_cvt_pk_bf16_f32 v141, v3, v4
	v_and_b32_e32 v4, 0xffff0000, v6
	v_lshlrev_b32_e32 v3, 16, v6
	v_mul_f32_e32 v4, 0x3e0293ee, v4
	v_mul_f32_e32 v3, 0x3e0293ee, v3
	v_cvt_pk_bf16_f32 v142, v3, v4
	v_and_b32_e32 v4, 0xffff0000, v7
	v_lshlrev_b32_e32 v3, 16, v7
	v_mul_f32_e32 v4, 0x3e0293ee, v4
	v_mul_f32_e32 v3, 0x3e0293ee, v3
	v_cvt_pk_bf16_f32 v143, v3, v4
	s_waitcnt vmcnt(3)
	v_mov_b32_e32 v4, v76
	v_mov_b32_e32 v5, v77
	v_mov_b32_e32 v6, v78
	v_mov_b32_e32 v7, v79
	v_lshlrev_b32_e32 v3, 16, v4
	v_and_b32_e32 v4, 0xffff0000, v4
	v_mul_f32_e32 v4, 0x3e0293ee, v4
	v_mul_f32_e32 v3, 0x3e0293ee, v3
	v_cvt_pk_bf16_f32 v144, v3, v4
	v_and_b32_e32 v4, 0xffff0000, v5
	v_lshlrev_b32_e32 v3, 16, v5
	v_mul_f32_e32 v4, 0x3e0293ee, v4
	v_mul_f32_e32 v3, 0x3e0293ee, v3
	v_cvt_pk_bf16_f32 v145, v3, v4
	v_and_b32_e32 v4, 0xffff0000, v6
	v_lshlrev_b32_e32 v3, 16, v6
	v_mul_f32_e32 v4, 0x3e0293ee, v4
	v_mul_f32_e32 v3, 0x3e0293ee, v3
	v_cvt_pk_bf16_f32 v146, v3, v4
	v_and_b32_e32 v4, 0xffff0000, v7
	v_lshlrev_b32_e32 v3, 16, v7
	v_mul_f32_e32 v4, 0x3e0293ee, v4
	v_mul_f32_e32 v3, 0x3e0293ee, v3
	v_cvt_pk_bf16_f32 v147, v3, v4
	s_waitcnt vmcnt(2)
; __device__ __forceinline__ int v_st(int k, int c) { const int kk = (k & ~0xC) | ((k & 4) << 1) | ((k & 8) >> 1); return ((kk >> 3) * 4 + (c >> 5)) * 512 + ((kk & 7) * 32 + (c & 31)) * 2; }
; __device__ __forceinline__ int v_rd_base(int lane) { return ((lane & 3) << 3) | (((lane >> 2) & 3) << 6) | (((lane >> 4) & 1) << 5) | (((lane >> 5) & 1) << 8); }
; #define SLOAD(i, k0) do { sr_[i].vs0 = ld8(&Vg[(long)((k0) + sr) * LDP + sc]); sr_[i].vs1 = ld8(&Vg[(long)((k0) + 32 + sr) * LDP + sc]); \
;     sr_[i].ks0 = ld8(&Kg[(long)((k0) + sr) * LDP + sc]); sr_[i].ks1 = ld8(&Kg[(long)((k0) + 32 + sr) * LDP + sc]); } while (0)
; #define SWRITE(off, i) do { *(bf16x8*)(V_lds + (off) + vst0) = sr_[i].vs0;          \
;     *(bf16x8*)(V_lds + (off) + vst1) = sr_[i].vs1; int kc = sc * 2;               \
;     *(bf16x8*)(K_lds + (off) + KSWZ(sr, kc)) = sr_[i].ks0;                       \
;     *(bf16x8*)(K_lds + (off) + KSWZ(32 + sr, kc)) = sr_[i].ks1; } while (0)
; template <int MODE, int ORD> ...
;     ...
;   for (int d0 = 0; d0 < ND0; ++d0) qr[d0] = scale_bf16x8(ld8(Qw + d0 * 16), C);
;   const int qpos = qpos0 + wq * 32 + r32;
;   const int qw0 = qpos0 + wq * 32;
;   const int cboff = cst * 128;
;   int sr = tid >> 4, sc = (tid & 15) * 8, vst0 = v_st(sr, sc), vst1 = v_st(32 + sr, sc);
;   int vb0 = (int)(uintptr_t)V_lds + v_rd_base(lane);
;   const bf16* Kg = Kh + (long)kbeg * LDP; const bf16* Vg = Vh + (long)kbeg * LDP;
;   struct { bf16x8 vs0, vs1, ks0, ks1; } sr_[1];
;     ...
;   float bL, bR, be_cur = 0.f; f32x16 negm;
; #pragma unroll
;   for (int r = 0; r < 16; ++r) negm[r] = -m_reg;
;     ...
;   SLOAD(SE, 0); asm volatile("s_waitcnt vmcnt(0)" ::: "memory"); SWRITE(0, SE); __syncthreads();
	v_mov_b32_e32 v4, v80
	v_mov_b32_e32 v5, v81
	v_mov_b32_e32 v6, v82
	v_mov_b32_e32 v7, v83
	v_lshlrev_b32_e32 v3, 16, v4
	v_and_b32_e32 v4, 0xffff0000, v4
	v_mul_f32_e32 v4, 0x3e0293ee, v4
	v_mul_f32_e32 v3, 0x3e0293ee, v3
	v_cvt_pk_bf16_f32 v148, v3, v4
	v_and_b32_e32 v4, 0xffff0000, v5
	v_lshlrev_b32_e32 v3, 16, v5
	v_mul_f32_e32 v4, 0x3e0293ee, v4
	v_mul_f32_e32 v3, 0x3e0293ee, v3
	v_cvt_pk_bf16_f32 v149, v3, v4
	v_and_b32_e32 v4, 0xffff0000, v6
	v_lshlrev_b32_e32 v3, 16, v6
	v_mul_f32_e32 v4, 0x3e0293ee, v4
	v_mul_f32_e32 v3, 0x3e0293ee, v3
	v_cvt_pk_bf16_f32 v150, v3, v4
	v_and_b32_e32 v4, 0xffff0000, v7
	v_lshlrev_b32_e32 v3, 16, v7
	v_mul_f32_e32 v4, 0x3e0293ee, v4
	v_mul_f32_e32 v3, 0x3e0293ee, v3
	v_cvt_pk_bf16_f32 v151, v3, v4
	s_waitcnt vmcnt(1)
	v_mov_b32_e32 v4, v84
	v_mov_b32_e32 v5, v85
	v_mov_b32_e32 v6, v86
	v_mov_b32_e32 v7, v87
	v_lshlrev_b32_e32 v3, 16, v4
	v_and_b32_e32 v4, 0xffff0000, v4
	v_mul_f32_e32 v4, 0x3e0293ee, v4
	v_mul_f32_e32 v3, 0x3e0293ee, v3
	v_cvt_pk_bf16_f32 v152, v3, v4
	v_and_b32_e32 v4, 0xffff0000, v5
	v_lshlrev_b32_e32 v3, 16, v5
	v_mul_f32_e32 v4, 0x3e0293ee, v4
	v_mul_f32_e32 v3, 0x3e0293ee, v3
	v_cvt_pk_bf16_f32 v153, v3, v4
	v_and_b32_e32 v4, 0xffff0000, v6
	v_lshlrev_b32_e32 v3, 16, v6
	v_mul_f32_e32 v4, 0x3e0293ee, v4
	v_mul_f32_e32 v3, 0x3e0293ee, v3
	v_cvt_pk_bf16_f32 v154, v3, v4
	v_and_b32_e32 v4, 0xffff0000, v7
	v_lshlrev_b32_e32 v3, 16, v7
	v_mul_f32_e32 v4, 0x3e0293ee, v4
	v_mul_f32_e32 v3, 0x3e0293ee, v3
	v_cvt_pk_bf16_f32 v155, v3, v4
	v_lshlrev_b32_e32 v3, 1, v179
	s_waitcnt vmcnt(0)
	v_mov_b32_e32 v4, v88
	v_mov_b32_e32 v5, v89
	v_mov_b32_e32 v6, v90
	v_mov_b32_e32 v7, v91
	v_and_b32_e32 v1, 0xffff0000, v4
	v_lshlrev_b32_e32 v0, 16, v4
	v_mul_f32_e32 v1, 0x3e0293ee, v1
	v_mul_f32_e32 v0, 0x3e0293ee, v0
	v_cvt_pk_bf16_f32 v156, v0, v1
	v_and_b32_e32 v1, 0xffff0000, v5
	v_lshlrev_b32_e32 v0, 16, v5
	v_mul_f32_e32 v1, 0x3e0293ee, v1
	v_mul_f32_e32 v0, 0x3e0293ee, v0
	v_cvt_pk_bf16_f32 v157, v0, v1
	v_and_b32_e32 v1, 0xffff0000, v6
	v_lshlrev_b32_e32 v0, 16, v6
	v_mul_f32_e32 v1, 0x3e0293ee, v1
	v_mul_f32_e32 v0, 0x3e0293ee, v0
	v_cvt_pk_bf16_f32 v158, v0, v1
	v_and_b32_e32 v1, 0xffff0000, v7
	v_lshlrev_b32_e32 v0, 16, v7
	v_mul_f32_e32 v1, 0x3e0293ee, v1
	v_mul_f32_e32 v0, 0x3e0293ee, v0
	v_cvt_pk_bf16_f32 v159, v0, v1
	v_and_b32_e32 v1, 0xfffff0, v179
	v_lshlrev_b32_e32 v0, 3, v48
	v_and_or_b32 v1, v3, 8, v1
	v_and_b32_e32 v180, 0x78, v0
	v_lshrrev_b32_e32 v1, 1, v1
	v_bfe_u32 v0, v0, 5, 2
	v_or_b32_e32 v1, v1, v0
	v_lshrrev_b32_e32 v3, 1, v179
	v_lshlrev_b32_e32 v17, 9, v1
	v_and_b32_e32 v1, 3, v179
	v_and_or_b32 v1, v3, 4, v1
	v_lshlrev_b32_e32 v18, 6, v1
	v_and_b32_e32 v1, 0xfffff0, v33
	v_lshlrev_b32_e32 v3, 1, v33
	v_and_or_b32 v1, v3, 8, v1
	v_lshrrev_b32_e32 v1, 1, v1
	v_lshlrev_b32_e32 v32, 1, v180
	v_or_b32_e32 v0, v1, v0
	v_lshlrev_b32_e32 v19, 9, v0
	v_and_b32_e32 v16, 48, v32
	v_or3_b32 v188, v17, v18, v16
	v_or3_b32 v189, v19, v18, v16
	v_mad_i64_i32 v[16:17], s[60:61], v179, s73, 0
	v_or_b32_e32 v16, v16, v180
	v_lshlrev_b64 v[24:25], 1, v[16:17]
	v_lshl_add_u64 v[16:17], s[42:43], 0, v[24:25]
	global_load_dwordx4 v[16:19], v[16:17], off
	v_or_b32_e32 v20, v20, v180
	v_lshlrev_b64 v[28:29], 1, v[20:21]
	v_lshl_add_u64 v[20:21], s[42:43], 0, v[28:29]
	v_lshl_add_u64 v[24:25], s[96:97], 0, v[24:25]
	v_lshl_add_u64 v[28:29], s[96:97], 0, v[28:29]
	global_load_dwordx4 v[20:23], v[20:21], off
	v_add_u32_e32 v49, 0, v188
	global_load_dwordx4 v[24:27], v[24:25], off
	v_add_u32_e32 v50, 0, v189
	global_load_dwordx4 v[28:31], v[28:29], off
	s_waitcnt vmcnt(0)
	v_mul_f32_e32 v0, 0xbfb8aa3b, v2
	v_mov_b32_e32 v1, v0
	v_mov_b32_e32 v2, v0
	v_mov_b32_e32 v3, v0
	v_mov_b32_e32 v4, v0
	v_mov_b32_e32 v5, v0
	v_mov_b32_e32 v6, v0
	v_mov_b32_e32 v7, v0
	v_mov_b32_e32 v8, v0
	v_mov_b32_e32 v9, v0
	v_mov_b32_e32 v10, v0
	v_mov_b32_e32 v11, v0
	v_mov_b32_e32 v12, v0
	v_mov_b32_e32 v13, v0
	v_mov_b32_e32 v14, v0
	v_mov_b32_e32 v15, v0
	s_waitcnt vmcnt(3)
	ds_write_b128 v49, v[16:19]
	v_lshlrev_b32_e32 v16, 8, v179
	v_and_b32_e32 v17, 0x70, v48
	v_bitop3_b32 v192, v32, v16, v17 bitop3:0xde
	v_lshlrev_b32_e32 v16, 8, v33
	v_bitop3_b32 v193, v32, v16, v17 bitop3:0xde
	v_lshlrev_b32_e32 v16, 4, v48
	v_and_b32_e32 v62, 0x70, v16
	v_bitop3_b32 v190, v204, v53, v62 bitop3:0xde
	v_add_u32_e32 v51, 0, v192
	v_add_u32_e32 v52, 0, v193
	v_add_u32_e32 v16, 0, v190
	s_waitcnt vmcnt(2)
	ds_write_b128 v50, v[20:23]
	s_waitcnt vmcnt(1)
	ds_write_b128 v51, v[24:27] offset:16384
	s_waitcnt vmcnt(0)
	ds_write_b128 v52, v[28:31] offset:16384
	s_waitcnt lgkmcnt(0)
	s_barrier
; template <int ND0> __device__ __forceinline__ void qkt(f32x16& p0, f32x16& p1, const char* Ks, const bf16x8* qr, int r32, int hi, int cboff, const f32x16& ci) {
; #pragma unroll
;   for (int d0 = 0; d0 < ND0; ++d0) { int cb = cboff + (d0 * 16 + hi * 8) * 2;
;     bf16x8 b0 = *reinterpret_cast<const bf16x8*>(Ks + KSWZ(r32, cb));
;     bf16x8 b1 = *reinterpret_cast<const bf16x8*>(Ks + KSWZ(32 + r32, cb));
;     if (d0 == 0) { p0 = __builtin_amdgcn_mfma_f32_32x32x16_bf16(b0, qr[0], ci, 0, 0, 0); p1 = __builtin_amdgcn_mfma_f32_32x32x16_bf16(b1, qr[0], ci, 0, 0, 0); }
;     else { p0 = __builtin_amdgcn_mfma_f32_32x32x16_bf16(b0, qr[d0], p0, 0, 0, 0); p1 = __builtin_amdgcn_mfma_f32_32x32x16_bf16(b1, qr[d0], p1, 0, 0, 0); } }
; }
	ds_read_b128 v[54:57], v16 offset:24576
	ds_read_b128 v[16:19], v16 offset:16384
	s_waitcnt lgkmcnt(0)
	v_mfma_f32_32x32x16_bf16 v[32:47], v[16:19], v[128:131], v[0:15]
	v_mfma_f32_32x32x16_bf16 v[16:31], v[54:57], v[128:131], v[0:15]
	v_or_b32_e32 v54, 32, v204
	v_bitop3_b32 v187, v54, v53, v62 bitop3:0xde
	v_add_u32_e32 v58, 0, v187
	ds_read_b128 v[54:57], v58 offset:24576
	ds_read_b128 v[58:61], v58 offset:16384
	s_waitcnt lgkmcnt(0)
	v_mfma_f32_32x32x16_bf16 v[32:47], v[58:61], v[132:135], v[32:47]
	v_mfma_f32_32x32x16_bf16 v[16:31], v[54:57], v[132:135], v[16:31]
	v_or_b32_e32 v54, 64, v204
	v_bitop3_b32 v186, v54, v53, v62 bitop3:0xde
	v_add_u32_e32 v58, 0, v186
	ds_read_b128 v[54:57], v58 offset:24576
	ds_read_b128 v[58:61], v58 offset:16384
	s_waitcnt lgkmcnt(0)
	v_mfma_f32_32x32x16_bf16 v[32:47], v[58:61], v[136:139], v[32:47]
	v_mfma_f32_32x32x16_bf16 v[16:31], v[54:57], v[136:139], v[16:31]
	v_or_b32_e32 v54, 0x60, v204
	v_bitop3_b32 v183, v54, v53, v62 bitop3:0xde
	v_add_u32_e32 v58, 0, v183
	ds_read_b128 v[54:57], v58 offset:24576
	ds_read_b128 v[58:61], v58 offset:16384
	s_waitcnt lgkmcnt(0)
	v_mfma_f32_32x32x16_bf16 v[32:47], v[58:61], v[140:143], v[32:47]
	v_mfma_f32_32x32x16_bf16 v[16:31], v[54:57], v[140:143], v[16:31]
	v_or_b32_e32 v54, 0x80, v204
	v_bitop3_b32 v184, v54, v53, v62 bitop3:0xde
	v_add_u32_e32 v58, 0, v184
	ds_read_b128 v[54:57], v58 offset:24576
	ds_read_b128 v[58:61], v58 offset:16384
	s_waitcnt lgkmcnt(0)
	v_mfma_f32_32x32x16_bf16 v[32:47], v[58:61], v[144:147], v[32:47]
	v_mfma_f32_32x32x16_bf16 v[16:31], v[54:57], v[144:147], v[16:31]
	v_or_b32_e32 v54, 0xa0, v204
	v_bitop3_b32 v185, v54, v53, v62 bitop3:0xde
	v_add_u32_e32 v58, 0, v185
	ds_read_b128 v[54:57], v58 offset:24576
	ds_read_b128 v[58:61], v58 offset:16384
	s_waitcnt lgkmcnt(0)
	v_mfma_f32_32x32x16_bf16 v[32:47], v[58:61], v[148:151], v[32:47]
	v_mfma_f32_32x32x16_bf16 v[16:31], v[54:57], v[148:151], v[16:31]
	v_or_b32_e32 v54, 0xc0, v204
	v_bitop3_b32 v182, v54, v53, v62 bitop3:0xde
	v_add_u32_e32 v58, 0, v182
	ds_read_b128 v[54:57], v58 offset:24576
	ds_read_b128 v[58:61], v58 offset:16384
	s_waitcnt lgkmcnt(0)
	v_mfma_f32_32x32x16_bf16 v[32:47], v[58:61], v[152:155], v[32:47]
	v_mfma_f32_32x32x16_bf16 v[16:31], v[54:57], v[152:155], v[16:31]
	v_or_b32_e32 v54, 0xe0, v204
	v_bitop3_b32 v181, v54, v53, v62 bitop3:0xde
	v_add_u32_e32 v53, 0, v181
	ds_read_b128 v[54:57], v53 offset:24576
	ds_read_b128 v[58:61], v53 offset:16384
	v_or_b32_e32 v53, s7, v191
	v_sub_u32_e32 v53, v53, v178
	s_waitcnt lgkmcnt(0)
	v_mfma_f32_32x32x16_bf16 v[32:47], v[58:61], v[156:159], v[32:47]
	v_mfma_f32_32x32x16_bf16 v[16:31], v[54:57], v[156:159], v[16:31]
	v_med3_i32 v55, v53, 0, v249
	v_lshl_add_u32 v57, v55, 2, s19
	ds_read_b32 v57, v57
	v_add_u32_e32 v54, 32, v53
	v_med3_i32 v56, v54, 0, v249
	v_cmp_eq_u32_e32 vcc, v53, v55
	s_waitcnt lgkmcnt(0)
	s_nop 3
	v_add_f32_e32 v32, v32, v57
	v_lshl_add_u32 v57, v56, 2, s19
	ds_read_b32 v57, v57
	s_waitcnt lgkmcnt(0)
	v_add_f32_e32 v57, v16, v57
	v_cndmask_b32_e32 v16, v251, v32, vcc
	v_add_u32_e32 v32, 1, v53
	v_cmp_eq_u32_e32 vcc, v54, v56
	v_med3_i32 v55, v32, 0, v249
	v_add_u32_e32 v54, 33, v53
	v_cndmask_b32_e32 v80, v251, v57, vcc
	v_lshl_add_u32 v57, v55, 2, s19
	ds_read_b32 v57, v57
	v_med3_i32 v56, v54, 0, v249
	v_cmp_eq_u32_e32 vcc, v32, v55
	v_add_u32_e32 v32, 2, v53
	s_waitcnt lgkmcnt(0)
	v_add_f32_e32 v33, v33, v57
	v_lshl_add_u32 v57, v56, 2, s19
	ds_read_b32 v57, v57
	s_waitcnt lgkmcnt(0)
	v_add_f32_e32 v57, v17, v57
	v_cndmask_b32_e32 v17, v251, v33, vcc
	v_cmp_eq_u32_e32 vcc, v54, v56
	v_med3_i32 v54, v32, 0, v249
	v_lshl_add_u32 v56, v54, 2, s19
	ds_read_b32 v56, v56
	v_add_u32_e32 v33, 34, v53
	v_med3_i32 v55, v33, 0, v249
	v_cndmask_b32_e32 v81, v251, v57, vcc
	v_cmp_eq_u32_e32 vcc, v32, v54
	s_waitcnt lgkmcnt(0)
	v_add_f32_e32 v34, v34, v56
	v_lshl_add_u32 v56, v55, 2, s19
	ds_read_b32 v56, v56
	v_add_u32_e32 v32, 3, v53
	s_waitcnt lgkmcnt(0)
	v_add_f32_e32 v56, v18, v56
	v_cndmask_b32_e32 v18, v251, v34, vcc
	v_med3_i32 v34, v32, 0, v249
	v_cmp_eq_u32_e32 vcc, v33, v55
	v_lshl_add_u32 v55, v34, 2, s19
	ds_read_b32 v55, v55
	v_add_u32_e32 v33, 35, v53
	v_med3_i32 v54, v33, 0, v249
	v_cndmask_b32_e32 v82, v251, v56, vcc
	v_cmp_eq_u32_e32 vcc, v32, v34
	s_waitcnt lgkmcnt(0)
	v_add_f32_e32 v35, v35, v55
	v_lshl_add_u32 v55, v54, 2, s19
	ds_read_b32 v55, v55
	v_add_u32_e32 v32, 8, v53
	v_med3_i32 v34, v32, 0, v249
	s_waitcnt lgkmcnt(0)
	v_add_f32_e32 v55, v19, v55
	v_cndmask_b32_e32 v19, v251, v35, vcc
	v_cmp_eq_u32_e32 vcc, v33, v54
	v_lshl_add_u32 v54, v34, 2, s19
	ds_read_b32 v54, v54
	v_add_u32_e32 v33, 40, v53
	v_med3_i32 v35, v33, 0, v249
	v_cndmask_b32_e32 v83, v251, v55, vcc
	v_cmp_eq_u32_e32 vcc, v32, v34
	s_waitcnt lgkmcnt(0)
	v_add_f32_e32 v36, v36, v54
	v_lshl_add_u32 v54, v35, 2, s19
	ds_read_b32 v54, v54
	v_add_u32_e32 v32, 9, v53
	v_med3_i32 v34, v32, 0, v249
	s_waitcnt lgkmcnt(0)
	v_add_f32_e32 v54, v20, v54
	v_cndmask_b32_e32 v20, v251, v36, vcc
	v_lshl_add_u32 v36, v34, 2, s19
	ds_read_b32 v36, v36
	v_cmp_eq_u32_e32 vcc, v33, v35
	v_add_u32_e32 v33, 41, v53
	v_med3_i32 v35, v33, 0, v249
	v_cndmask_b32_e32 v84, v251, v54, vcc
	s_waitcnt lgkmcnt(0)
	v_add_f32_e32 v36, v37, v36
	v_lshl_add_u32 v37, v35, 2, s19
	ds_read_b32 v37, v37
	v_cmp_eq_u32_e32 vcc, v32, v34
	v_add_u32_e32 v32, 10, v53
	v_med3_i32 v34, v32, 0, v249
	s_waitcnt lgkmcnt(0)
; __device__ __forceinline__ float max3f(float a, float b, float c) { float r; asm("v_max3_f32 %0, %1, %2, %3" : "=v"(r) : "v"(a), "v"(b), "v"(c)); return r; }
; template <bool FIRST> __device__ __forceinline__ void partialSM2(f32x16& p0, f32x16& p1, float& m_ref, f32x16& negm, float& alpha) {
;   float pmax = max3f(p0[0], p0[1], p1[0]), pmb = max3f(p0[2], p0[3], p1[1]);
;   pmax = max3f(pmax, p1[2], p1[3]);
; #pragma unroll
;   for (int r = 4; r < 16; r += 4) { pmax = max3f(pmax, p0[r], p0[r + 1]); pmb = max3f(pmb, p0[r + 2], p0[r + 3]); pmax = max3f(pmax, p1[r], p1[r + 1]); pmb = max3f(pmb, p1[r + 2], p1[r + 3]); }
;   pmax = max3f(pmax, pmb, pmb);
;   { auto rr = __builtin_amdgcn_permlane32_swap(__float_as_uint(pmax), __float_as_uint(pmax), false, false);
;     pmax = fmaxf(__uint_as_float(rr[0]), __uint_as_float(rr[1])); }
;   alpha = 1.f;
;   if (FIRST || !__builtin_expect(__all(pmax <= THR), 1)) {
	v_add_f32_e32 v37, v21, v37
	v_cndmask_b32_e32 v21, v251, v36, vcc
	v_cmp_eq_u32_e32 vcc, v33, v35
	v_add_u32_e32 v33, 42, v53
	v_med3_i32 v35, v33, 0, v249
	v_lshl_add_u32 v36, v34, 2, s19
	v_cndmask_b32_e32 v85, v251, v37, vcc
	ds_read_b32 v36, v36
	v_lshl_add_u32 v37, v35, 2, s19
	ds_read_b32 v37, v37
	v_cmp_eq_u32_e32 vcc, v32, v34
	v_add_u32_e32 v32, 11, v53
	s_waitcnt lgkmcnt(1)
	v_add_f32_e32 v36, v38, v36
	v_med3_i32 v34, v32, 0, v249
	s_waitcnt lgkmcnt(0)
	v_add_f32_e32 v37, v22, v37
	v_cndmask_b32_e32 v22, v251, v36, vcc
	v_cmp_eq_u32_e32 vcc, v33, v35
	v_add_u32_e32 v33, 43, v53
	v_med3_i32 v35, v33, 0, v249
	v_lshl_add_u32 v36, v34, 2, s19
	v_cndmask_b32_e32 v86, v251, v37, vcc
	ds_read_b32 v36, v36
	v_lshl_add_u32 v37, v35, 2, s19
	ds_read_b32 v37, v37
	v_cmp_eq_u32_e32 vcc, v32, v34
	v_add_u32_e32 v32, 16, v53
	s_waitcnt lgkmcnt(1)
	v_add_f32_e32 v36, v39, v36
	v_med3_i32 v34, v32, 0, v249
	s_waitcnt lgkmcnt(0)
	v_add_f32_e32 v37, v23, v37
	v_cndmask_b32_e32 v23, v251, v36, vcc
	v_cmp_eq_u32_e32 vcc, v33, v35
	v_add_u32_e32 v33, 48, v53
	v_med3_i32 v35, v33, 0, v249
	v_lshl_add_u32 v36, v34, 2, s19
	v_cndmask_b32_e32 v87, v251, v37, vcc
	ds_read_b32 v36, v36
	v_lshl_add_u32 v37, v35, 2, s19
	ds_read_b32 v37, v37
	v_cmp_eq_u32_e32 vcc, v32, v34
	v_add_u32_e32 v32, 17, v53
	s_waitcnt lgkmcnt(1)
	v_add_f32_e32 v36, v40, v36
	v_med3_i32 v34, v32, 0, v249
	s_waitcnt lgkmcnt(0)
	v_add_f32_e32 v37, v24, v37
	v_cndmask_b32_e32 v24, v251, v36, vcc
	v_cmp_eq_u32_e32 vcc, v33, v35
	v_add_u32_e32 v33, 49, v53
	v_med3_i32 v35, v33, 0, v249
	v_lshl_add_u32 v36, v34, 2, s19
	v_cndmask_b32_e32 v88, v251, v37, vcc
	ds_read_b32 v36, v36
	v_lshl_add_u32 v37, v35, 2, s19
	ds_read_b32 v37, v37
	v_cmp_eq_u32_e32 vcc, v32, v34
	v_add_u32_e32 v32, 18, v53
	s_waitcnt lgkmcnt(1)
	v_add_f32_e32 v36, v41, v36
	v_med3_i32 v34, v32, 0, v249
	s_waitcnt lgkmcnt(0)
	v_add_f32_e32 v37, v25, v37
	v_cndmask_b32_e32 v25, v251, v36, vcc
	v_cmp_eq_u32_e32 vcc, v33, v35
	v_add_u32_e32 v33, 50, v53
	v_med3_i32 v35, v33, 0, v249
	v_lshl_add_u32 v36, v34, 2, s19
	v_cndmask_b32_e32 v89, v251, v37, vcc
	ds_read_b32 v36, v36
	v_lshl_add_u32 v37, v35, 2, s19
	ds_read_b32 v37, v37
	v_cmp_eq_u32_e32 vcc, v32, v34
	v_add_u32_e32 v32, 19, v53
	s_waitcnt lgkmcnt(1)
	v_add_f32_e32 v36, v42, v36
	v_med3_i32 v34, v32, 0, v249
	s_waitcnt lgkmcnt(0)
	v_add_f32_e32 v37, v26, v37
	v_cndmask_b32_e32 v26, v251, v36, vcc
	v_cmp_eq_u32_e32 vcc, v33, v35
	v_add_u32_e32 v33, 51, v53
	v_med3_i32 v35, v33, 0, v249
	v_lshl_add_u32 v36, v34, 2, s19
	v_cndmask_b32_e32 v90, v251, v37, vcc
	ds_read_b32 v36, v36
	v_lshl_add_u32 v37, v35, 2, s19
	ds_read_b32 v37, v37
	v_cmp_eq_u32_e32 vcc, v32, v34
	v_add_u32_e32 v32, 24, v53
	s_waitcnt lgkmcnt(1)
	v_add_f32_e32 v36, v43, v36
	v_med3_i32 v34, v32, 0, v249
	s_waitcnt lgkmcnt(0)
	v_add_f32_e32 v37, v27, v37
	v_cndmask_b32_e32 v27, v251, v36, vcc
	v_cmp_eq_u32_e32 vcc, v33, v35
	v_add_u32_e32 v33, 56, v53
	v_med3_i32 v35, v33, 0, v249
	v_lshl_add_u32 v36, v34, 2, s19
	v_cndmask_b32_e32 v91, v251, v37, vcc
	ds_read_b32 v36, v36
	v_lshl_add_u32 v37, v35, 2, s19
	ds_read_b32 v37, v37
	v_cmp_eq_u32_e32 vcc, v32, v34
	v_add_u32_e32 v32, 25, v53
	s_waitcnt lgkmcnt(1)
	v_add_f32_e32 v36, v44, v36
	v_med3_i32 v34, v32, 0, v249
	s_waitcnt lgkmcnt(0)
	v_add_f32_e32 v37, v28, v37
	v_cndmask_b32_e32 v28, v251, v36, vcc
	v_cmp_eq_u32_e32 vcc, v33, v35
	v_add_u32_e32 v33, 57, v53
	v_med3_i32 v35, v33, 0, v249
	v_lshl_add_u32 v36, v34, 2, s19
	v_cndmask_b32_e32 v92, v251, v37, vcc
	ds_read_b32 v36, v36
	v_lshl_add_u32 v37, v35, 2, s19
	ds_read_b32 v37, v37
	v_cmp_eq_u32_e32 vcc, v32, v34
	v_add_u32_e32 v32, 26, v53
	s_waitcnt lgkmcnt(1)
	v_add_f32_e32 v36, v45, v36
	v_med3_i32 v34, v32, 0, v249
	s_waitcnt lgkmcnt(0)
	v_add_f32_e32 v37, v29, v37
	v_cndmask_b32_e32 v29, v251, v36, vcc
	v_cmp_eq_u32_e32 vcc, v33, v35
	v_add_u32_e32 v33, 58, v53
	v_med3_i32 v35, v33, 0, v249
	v_lshl_add_u32 v36, v34, 2, s19
	v_cndmask_b32_e32 v93, v251, v37, vcc
	ds_read_b32 v36, v36
	v_lshl_add_u32 v37, v35, 2, s19
	ds_read_b32 v37, v37
	v_cmp_eq_u32_e32 vcc, v32, v34
	v_add_u32_e32 v32, 59, v53
	s_waitcnt lgkmcnt(1)
	v_add_f32_e32 v36, v46, v36
	s_waitcnt lgkmcnt(0)
	v_add_f32_e32 v37, v30, v37
	v_cndmask_b32_e32 v30, v251, v36, vcc
	v_cmp_eq_u32_e32 vcc, v33, v35
	v_add_u32_e32 v33, 27, v53
	v_med3_i32 v34, v33, 0, v249
	v_med3_i32 v35, v32, 0, v249
	v_lshl_add_u32 v36, v34, 2, s19
	v_cndmask_b32_e32 v94, v251, v37, vcc
	ds_read_b32 v36, v36
	v_lshl_add_u32 v37, v35, 2, s19
	ds_read_b32 v37, v37
	v_cmp_eq_u32_e32 vcc, v33, v34
	v_max3_f32 v33, v18, v19, v81
	s_waitcnt lgkmcnt(1)
	v_add_f32_e32 v36, v47, v36
	v_max3_f32 v33, v33, v22, v23
	s_waitcnt lgkmcnt(0)
	v_add_f32_e32 v37, v31, v37
	v_cndmask_b32_e32 v31, v251, v36, vcc
	v_cmp_eq_u32_e32 vcc, v32, v35
	v_max3_f32 v32, v16, v17, v80
	v_max3_f32 v33, v33, v86, v87
	s_nop 0
	v_max3_f32 v32, v32, v82, v83
	v_max3_f32 v33, v33, v26, v27
	s_nop 0
	v_cndmask_b32_e32 v95, v251, v37, vcc
	v_max3_f32 v32, v32, v20, v21
	v_max3_f32 v33, v33, v90, v91
	s_nop 0
	v_max3_f32 v32, v32, v84, v85
	v_max3_f32 v33, v33, v30, v31
	s_nop 0
	v_max3_f32 v32, v32, v24, v25
	v_max3_f32 v33, v33, v94, v95
	s_nop 0
	v_max3_f32 v32, v32, v88, v89
	s_nop 0
	v_max3_f32 v32, v32, v28, v29
	s_nop 0
	v_max3_f32 v32, v32, v92, v93
	s_nop 0
	v_max3_f32 v32, v32, v33, v33
	s_nop 0
	v_mov_b32_e32 v33, v32
	s_nop 1
	v_permlane32_swap_b32_e32 v32, v33
	v_max_f32_e32 v33, v33, v33
	v_max_f32_e32 v32, v32, v32
	v_max_f32_e32 v32, v32, v33
	v_cmp_ge_f32_e32 vcc, s76, v32
	s_cmp_eq_u64 vcc, exec
	s_cbranch_scc0 .LBB0_243
	v_mov_b32_e32 v196, 1.0
